# gla_g1: prefetch the 32 wave-uniform low-rank-decay loads 4 tokens ahead with counted waits (were 32 serialized vmcnt(0) round trips per unit)
# speedup vs baseline: 1.0123x; 1.0047x over previous
.LBB0_1027:
	s_bfe_u32 s10, s11, 0x20006
	s_and_b32 s12, s8, 0xfffff000
	s_and_b32 s18, s1, 0xfc0
	s_or_b32 s12, s12, s18
	s_lshl_b32 s18, s10, 6
	v_add_u32_e32 v2, s12, v44
	v_mov_b64_e32 v[26:27], s[56:57]
	v_or_b32_e32 v28, s18, v33
	v_mad_i64_i32 v[2:3], s[34:35], v2, s20, v[26:27]
	s_lshl_b32 s90, s10, 8
	v_lshlrev_b32_e32 v42, 2, v28
	v_mov_b32_e32 v43, v1
	v_lshl_add_u64 v[4:5], v[2:3], 0, s[90:91]
	s_lshl_b32 s90, s10, 9
	v_lshl_add_u64 v[60:61], s[4:5], 0, v[42:43]
	s_movk_i32 s10, 0x1000
	v_add_co_u32_e64 v28, s[52:53], s10, v60
	v_lshl_add_u64 v[2:3], v[2:3], 0, s[90:91]
	s_nop 0
	v_addc_co_u32_e64 v29, s[52:53], 0, v61, s[52:53]
	v_mov_b32_e32 v41, v1
	v_add_co_u32_e64 v62, s[52:53], s28, v60
	v_lshl_add_u64 v[4:5], v[4:5], 0, v[0:1]
	v_lshl_add_u64 v[2:3], v[2:3], 0, v[40:41]
	v_addc_co_u32_e64 v63, s[52:53], 0, v61, s[52:53]
	s_movk_i32 s10, 0x3000
	flat_load_dwordx4 v[22:25], v[4:5] offset:1024
	flat_load_dwordx4 v[18:21], v[4:5] offset:1040
	flat_load_dwordx4 v[14:17], v[2:3] offset:2048
	flat_load_dwordx4 v[10:13], v[2:3] offset:2064
	flat_load_dwordx4 v[6:9], v[2:3] offset:2080
	s_nop 0
	flat_load_dwordx4 v[2:5], v[2:3] offset:2096
	s_nop 0
	global_load_dword v70, v42, s[4:5]
	global_load_dword v73, v42, s[4:5] offset:1024
	global_load_dword v71, v42, s[4:5] offset:2048
	global_load_dword v72, v42, s[4:5] offset:3072
	global_load_dword v66, v[62:63], off offset:-4096
	global_load_dword v69, v[28:29], off offset:1024
	global_load_dword v67, v[28:29], off offset:2048
	global_load_dword v68, v[28:29], off offset:3072
	s_nop 0
	global_load_dword v28, v[62:63], off
	global_load_dword v65, v[62:63], off offset:1024
	global_load_dword v29, v[62:63], off offset:2048
	global_load_dword v64, v[62:63], off offset:3072
	v_add_co_u32_e64 v62, s[52:53], s10, v60
	s_mov_b32 s26, 0xbfb8aa3b
	s_nop 0
	v_addc_co_u32_e64 v63, s[52:53], 0, v61, s[52:53]
	global_load_dword v43, v[62:63], off
	global_load_dword v61, v[62:63], off offset:1024
	global_load_dword v60, v[62:63], off offset:2048
	global_load_dword v41, v[62:63], off offset:3072
	global_load_dword v74, v42, s[6:7]
	v_add_u32_e32 v42, s12, v45
	v_mad_i64_i32 v[62:63], s[34:35], v42, s20, v[26:27]
	v_add_co_u32_e64 v62, s[52:53], s13, v62
	s_mov_b32 s27, 0x3f317217
	s_nop 0
	v_addc_co_u32_e64 v63, s[52:53], 0, v63, s[52:53]
	v_mad_i64_i32 v[150:151], s[34:35], v42, s20, v[26:27]
	v_add_co_u32_e64 v150, s[52:53], s13, v150
	s_nop 1
	v_addc_co_u32_e64 v151, s[52:53], 0, v151, s[52:53]
	v_or_b32_e32 v166, 1, v42
	v_mad_i64_i32 v[152:153], s[34:35], v166, s20, v[26:27]
	v_add_co_u32_e64 v152, s[52:53], s13, v152
	s_nop 1
	v_addc_co_u32_e64 v153, s[52:53], 0, v153, s[52:53]
	v_or_b32_e32 v166, 2, v42
	v_mad_i64_i32 v[154:155], s[34:35], v166, s20, v[26:27]
	v_add_co_u32_e64 v154, s[52:53], s13, v154
	s_nop 1
	v_addc_co_u32_e64 v155, s[52:53], 0, v155, s[52:53]
	v_or_b32_e32 v166, 3, v42
	v_mad_i64_i32 v[156:157], s[34:35], v166, s20, v[26:27]
	v_add_co_u32_e64 v156, s[52:53], s13, v156
	s_nop 1
	v_addc_co_u32_e64 v157, s[52:53], 0, v157, s[52:53]
	v_or_b32_e32 v166, 4, v42
	v_mad_i64_i32 v[158:159], s[34:35], v166, s20, v[26:27]
	v_add_co_u32_e64 v158, s[52:53], s13, v158
	s_nop 1
	v_addc_co_u32_e64 v159, s[52:53], 0, v159, s[52:53]
	v_or_b32_e32 v166, 5, v42
	v_mad_i64_i32 v[160:161], s[34:35], v166, s20, v[26:27]
	v_add_co_u32_e64 v160, s[52:53], s13, v160
	s_nop 1
	v_addc_co_u32_e64 v161, s[52:53], 0, v161, s[52:53]
	v_or_b32_e32 v166, 6, v42
	v_mad_i64_i32 v[162:163], s[34:35], v166, s20, v[26:27]
	v_add_co_u32_e64 v162, s[52:53], s13, v162
	s_nop 1
	v_addc_co_u32_e64 v163, s[52:53], 0, v163, s[52:53]
	v_or_b32_e32 v166, 7, v42
	v_mad_i64_i32 v[164:165], s[34:35], v166, s20, v[26:27]
	v_add_co_u32_e64 v164, s[52:53], s13, v164
	s_nop 1
	v_addc_co_u32_e64 v165, s[52:53], 0, v165, s[52:53]
	global_load_dwordx4 v[86:89], v[150:151], off offset:1024
	global_load_dwordx4 v[90:93], v[150:151], off offset:1040
	global_load_dwordx4 v[94:97], v[150:151], off offset:1056
	global_load_dwordx4 v[98:101], v[150:151], off offset:1072
	global_load_dwordx4 v[102:105], v[152:153], off offset:1024
	global_load_dwordx4 v[106:109], v[152:153], off offset:1040
	global_load_dwordx4 v[110:113], v[152:153], off offset:1056
	global_load_dwordx4 v[114:117], v[152:153], off offset:1072
	global_load_dwordx4 v[118:121], v[154:155], off offset:1024
	global_load_dwordx4 v[122:125], v[154:155], off offset:1040
	global_load_dwordx4 v[126:129], v[154:155], off offset:1056
	global_load_dwordx4 v[130:133], v[154:155], off offset:1072
	global_load_dwordx4 v[134:137], v[156:157], off offset:1024
	global_load_dwordx4 v[138:141], v[156:157], off offset:1040
	global_load_dwordx4 v[142:145], v[156:157], off offset:1056
	global_load_dwordx4 v[146:149], v[156:157], off offset:1072
	s_mov_b32 s28, 0x7f800000
	s_mov_b32 s10, 0x3d800000
	s_waitcnt vmcnt(12) lgkmcnt(0)
	v_mov_b32_e32 v76, v86
	v_mov_b32_e32 v77, v87
	v_mov_b32_e32 v78, v88
	v_mov_b32_e32 v79, v89
	v_mul_f32_e32 v75, v73, v77
	v_fmac_f32_e32 v75, v70, v76
	v_fmac_f32_e32 v75, v71, v78
	v_fmac_f32_e32 v75, v72, v79
	v_add_f32_e32 v75, v74, v75
	v_mov_b32_e32 v76, v90
	v_mov_b32_e32 v77, v91
	v_mov_b32_e32 v78, v92
	v_mov_b32_e32 v79, v93
	v_mul_f32_e32 v77, v69, v77
	v_fmac_f32_e32 v77, v66, v76
	v_fmac_f32_e32 v77, v67, v78
	v_fmac_f32_e32 v77, v68, v79
	v_add_f32_e32 v75, v75, v77
	v_mov_b32_e32 v76, v94
	v_mov_b32_e32 v77, v95
	v_mov_b32_e32 v78, v96
	v_mov_b32_e32 v79, v97
	v_mul_f32_e32 v77, v65, v77
	v_fmac_f32_e32 v77, v28, v76
	v_fmac_f32_e32 v77, v29, v78
	v_fmac_f32_e32 v77, v64, v79
	v_add_f32_e32 v75, v75, v77
	v_mov_b32_e32 v76, v98
	v_mov_b32_e32 v77, v99
	v_mov_b32_e32 v78, v100
	v_mov_b32_e32 v79, v101
	global_load_dwordx4 v[86:89], v[158:159], off offset:1024
	global_load_dwordx4 v[90:93], v[158:159], off offset:1040
	global_load_dwordx4 v[94:97], v[158:159], off offset:1056
	global_load_dwordx4 v[98:101], v[158:159], off offset:1072
	v_mul_f32_e32 v62, v61, v77
	v_fmac_f32_e32 v62, v43, v76
	v_fmac_f32_e32 v62, v60, v78
	v_fmac_f32_e32 v62, v41, v79
	v_add_f32_e32 v62, v75, v62
	v_min_f32_e32 v63, 0, v62
	v_mul_f32_e64 v62, |v62|, s26
	v_exp_f32_e32 v62, v62
	s_nop 0
	v_add_f32_e32 v62, 1.0, v62
	v_cmp_gt_f32_e64 s[52:53], s19, v62
	s_nop 1
	v_cndmask_b32_e64 v75, 0, 32, s[52:53]
	v_ldexp_f32 v62, v62, v75
	v_log_f32_e32 v62, v62
	s_nop 0
	v_mul_f32_e32 v75, 0x3f317217, v62
	v_fma_f32 v75, v62, s27, -v75
	v_fmac_f32_e32 v75, 0x3377d1cf, v62
	v_fmac_f32_e32 v75, 0x3f317217, v62
	v_cmp_lt_f32_e64 s[54:55], |v62|, s28
	s_nop 1
	v_cndmask_b32_e64 v62, v62, v75, s[54:55]
	v_cndmask_b32_e64 v75, 0, v228, s[52:53]
	v_sub_f32_e32 v62, v62, v75
	v_sub_f32_e32 v62, v63, v62
	v_or_b32_e32 v63, 1, v42
	v_mad_i64_i32 v[76:77], s[34:35], v63, s20, v[26:27]
	v_add_co_u32_e64 v80, s[52:53], s13, v76
	v_fma_f32 v62, v62, s10, 0
	s_nop 0
	v_addc_co_u32_e64 v81, s[52:53], 0, v77, s[52:53]
	s_waitcnt vmcnt(12) lgkmcnt(0)
	v_mov_b32_e32 v76, v102
	v_mov_b32_e32 v77, v103
	v_mov_b32_e32 v78, v104
	v_mov_b32_e32 v79, v105
	v_mul_f32_e32 v63, v73, v77
	v_fmac_f32_e32 v63, v70, v76
	v_fmac_f32_e32 v63, v71, v78
	v_fmac_f32_e32 v63, v72, v79
	v_add_f32_e32 v63, v74, v63
	v_mov_b32_e32 v76, v106
	v_mov_b32_e32 v77, v107
	v_mov_b32_e32 v78, v108
	v_mov_b32_e32 v79, v109
	v_mul_f32_e32 v75, v69, v77
	v_fmac_f32_e32 v75, v66, v76
	v_fmac_f32_e32 v75, v67, v78
	v_fmac_f32_e32 v75, v68, v79
	v_add_f32_e32 v63, v63, v75
	v_mov_b32_e32 v76, v110
	v_mov_b32_e32 v77, v111
	v_mov_b32_e32 v78, v112
	v_mov_b32_e32 v79, v113
	v_mul_f32_e32 v75, v65, v77
	v_fmac_f32_e32 v75, v28, v76
	v_fmac_f32_e32 v75, v29, v78
	v_fmac_f32_e32 v75, v64, v79
	v_add_f32_e32 v63, v63, v75
	v_mov_b32_e32 v76, v114
	v_mov_b32_e32 v77, v115
	v_mov_b32_e32 v78, v116
	v_mov_b32_e32 v79, v117
	global_load_dwordx4 v[102:105], v[160:161], off offset:1024
	global_load_dwordx4 v[106:109], v[160:161], off offset:1040
	global_load_dwordx4 v[110:113], v[160:161], off offset:1056
	global_load_dwordx4 v[114:117], v[160:161], off offset:1072
	v_mul_f32_e32 v75, v61, v77
	v_fmac_f32_e32 v75, v43, v76
	v_fmac_f32_e32 v75, v60, v78
	v_fmac_f32_e32 v75, v41, v79
	v_add_f32_e32 v63, v63, v75
	v_min_f32_e32 v75, 0, v63
	v_mul_f32_e64 v63, |v63|, s26
	v_exp_f32_e32 v63, v63
	s_nop 0
	v_add_f32_e32 v63, 1.0, v63
	v_cmp_gt_f32_e64 s[52:53], s19, v63
	s_nop 1
	v_cndmask_b32_e64 v76, 0, 32, s[52:53]
	v_ldexp_f32 v63, v63, v76
	v_log_f32_e32 v63, v63
	s_nop 0
	v_mul_f32_e32 v76, 0x3f317217, v63
	v_fma_f32 v76, v63, s27, -v76
	v_fmac_f32_e32 v76, 0x3377d1cf, v63
	v_fmac_f32_e32 v76, 0x3f317217, v63
	v_cmp_lt_f32_e64 s[54:55], |v63|, s28
	s_nop 1
	v_cndmask_b32_e64 v63, v63, v76, s[54:55]
	v_cndmask_b32_e64 v76, 0, v228, s[52:53]
	v_sub_f32_e32 v63, v63, v76
	v_sub_f32_e32 v63, v75, v63
	v_or_b32_e32 v75, 2, v42
	v_mad_i64_i32 v[76:77], s[34:35], v75, s20, v[26:27]
	v_add_co_u32_e64 v80, s[52:53], s13, v76
	v_fmamk_f32 v63, v63, 0x3d800000, v62
	s_nop 0
	v_addc_co_u32_e64 v81, s[52:53], 0, v77, s[52:53]
	s_waitcnt vmcnt(12) lgkmcnt(0)
	v_mov_b32_e32 v76, v118
	v_mov_b32_e32 v77, v119
	v_mov_b32_e32 v78, v120
	v_mov_b32_e32 v79, v121
	v_mul_f32_e32 v75, v73, v77
	v_fmac_f32_e32 v75, v70, v76
	v_fmac_f32_e32 v75, v71, v78
	v_fmac_f32_e32 v75, v72, v79
	v_add_f32_e32 v75, v74, v75
	v_mov_b32_e32 v76, v122
	v_mov_b32_e32 v77, v123
	v_mov_b32_e32 v78, v124
	v_mov_b32_e32 v79, v125
	v_mul_f32_e32 v77, v69, v77
	v_fmac_f32_e32 v77, v66, v76
	v_fmac_f32_e32 v77, v67, v78
	v_fmac_f32_e32 v77, v68, v79
	v_add_f32_e32 v75, v75, v77
	v_mov_b32_e32 v76, v126
	v_mov_b32_e32 v77, v127
	v_mov_b32_e32 v78, v128
	v_mov_b32_e32 v79, v129
	v_mul_f32_e32 v77, v65, v77
	v_fmac_f32_e32 v77, v28, v76
	v_fmac_f32_e32 v77, v29, v78
	v_fmac_f32_e32 v77, v64, v79
	v_add_f32_e32 v75, v75, v77
	v_mov_b32_e32 v76, v130
	v_mov_b32_e32 v77, v131
	v_mov_b32_e32 v78, v132
	v_mov_b32_e32 v79, v133
	global_load_dwordx4 v[118:121], v[162:163], off offset:1024
	global_load_dwordx4 v[122:125], v[162:163], off offset:1040
	global_load_dwordx4 v[126:129], v[162:163], off offset:1056
	global_load_dwordx4 v[130:133], v[162:163], off offset:1072
	v_mul_f32_e32 v77, v61, v77
	v_fmac_f32_e32 v77, v43, v76
	v_fmac_f32_e32 v77, v60, v78
	v_fmac_f32_e32 v77, v41, v79
	v_add_f32_e32 v75, v75, v77
	v_min_f32_e32 v76, 0, v75
	v_mul_f32_e64 v75, |v75|, s26
	v_exp_f32_e32 v75, v75
	s_nop 0
	v_add_f32_e32 v75, 1.0, v75
	v_cmp_gt_f32_e64 s[52:53], s19, v75
	s_nop 1
	v_cndmask_b32_e64 v77, 0, 32, s[52:53]
	v_ldexp_f32 v75, v75, v77
	v_log_f32_e32 v75, v75
	s_nop 0
	v_mul_f32_e32 v77, 0x3f317217, v75
	v_fma_f32 v77, v75, s27, -v77
	v_fmac_f32_e32 v77, 0x3377d1cf, v75
	v_fmac_f32_e32 v77, 0x3f317217, v75
	v_cmp_lt_f32_e64 s[54:55], |v75|, s28
	s_nop 1
	v_cndmask_b32_e64 v75, v75, v77, s[54:55]
	v_cndmask_b32_e64 v77, 0, v228, s[52:53]
	v_sub_f32_e32 v75, v75, v77
	v_sub_f32_e32 v75, v76, v75
	v_or_b32_e32 v76, 3, v42
	v_mad_i64_i32 v[76:77], s[34:35], v76, s20, v[26:27]
	v_add_co_u32_e64 v80, s[52:53], s13, v76
	v_fmamk_f32 v75, v75, 0x3d800000, v63
	s_nop 0
	v_addc_co_u32_e64 v81, s[52:53], 0, v77, s[52:53]
	s_waitcnt vmcnt(12) lgkmcnt(0)
	v_mov_b32_e32 v76, v134
	v_mov_b32_e32 v77, v135
	v_mov_b32_e32 v78, v136
	v_mov_b32_e32 v79, v137
	v_mul_f32_e32 v77, v73, v77
	v_fmac_f32_e32 v77, v70, v76
	v_fmac_f32_e32 v77, v71, v78
	v_fmac_f32_e32 v77, v72, v79
	v_add_f32_e32 v82, v74, v77
	v_mov_b32_e32 v76, v138
	v_mov_b32_e32 v77, v139
	v_mov_b32_e32 v78, v140
	v_mov_b32_e32 v79, v141
	v_mul_f32_e32 v77, v69, v77
	v_fmac_f32_e32 v77, v66, v76
	v_fmac_f32_e32 v77, v67, v78
	v_fmac_f32_e32 v77, v68, v79
	v_add_f32_e32 v82, v82, v77
	v_mov_b32_e32 v76, v142
	v_mov_b32_e32 v77, v143
	v_mov_b32_e32 v78, v144
	v_mov_b32_e32 v79, v145
	v_mul_f32_e32 v77, v65, v77
	v_fmac_f32_e32 v77, v28, v76
	v_fmac_f32_e32 v77, v29, v78
	v_fmac_f32_e32 v77, v64, v79
	v_add_f32_e32 v82, v82, v77
	v_mov_b32_e32 v76, v146
	v_mov_b32_e32 v77, v147
	v_mov_b32_e32 v78, v148
	v_mov_b32_e32 v79, v149
	global_load_dwordx4 v[134:137], v[164:165], off offset:1024
	global_load_dwordx4 v[138:141], v[164:165], off offset:1040
	global_load_dwordx4 v[142:145], v[164:165], off offset:1056
	global_load_dwordx4 v[146:149], v[164:165], off offset:1072
	v_mul_f32_e32 v77, v61, v77
	v_fmac_f32_e32 v77, v43, v76
	v_fmac_f32_e32 v77, v60, v78
	v_fmac_f32_e32 v77, v41, v79
	v_add_f32_e32 v76, v82, v77
	v_min_f32_e32 v77, 0, v76
	v_mul_f32_e64 v76, |v76|, s26
	v_exp_f32_e32 v76, v76
	s_nop 0
	v_add_f32_e32 v76, 1.0, v76
	v_cmp_gt_f32_e64 s[52:53], s19, v76
	s_nop 1
	v_cndmask_b32_e64 v78, 0, 32, s[52:53]
	v_ldexp_f32 v76, v76, v78
	v_log_f32_e32 v76, v76
	s_nop 0
	v_mul_f32_e32 v78, 0x3f317217, v76
	v_fma_f32 v78, v76, s27, -v78
	v_fmac_f32_e32 v78, 0x3377d1cf, v76
	v_fmac_f32_e32 v78, 0x3f317217, v76
	v_cmp_lt_f32_e64 s[54:55], |v76|, s28
	s_nop 1
	v_cndmask_b32_e64 v76, v76, v78, s[54:55]
	v_cndmask_b32_e64 v78, 0, v228, s[52:53]
	v_sub_f32_e32 v76, v76, v78
	v_sub_f32_e32 v76, v77, v76
	v_or_b32_e32 v77, 4, v42
	v_mad_i64_i32 v[78:79], s[34:35], v77, s20, v[26:27]
	v_add_co_u32_e64 v82, s[52:53], s13, v78
	v_fmamk_f32 v76, v76, 0x3d800000, v75
	s_nop 0
	v_addc_co_u32_e64 v83, s[52:53], 0, v79, s[52:53]
	s_waitcnt vmcnt(12) lgkmcnt(0)
	v_mov_b32_e32 v78, v86
	v_mov_b32_e32 v79, v87
	v_mov_b32_e32 v80, v88
	v_mov_b32_e32 v81, v89
	v_mul_f32_e32 v77, v73, v79
	v_fmac_f32_e32 v77, v70, v78
	v_fmac_f32_e32 v77, v71, v80
	v_fmac_f32_e32 v77, v72, v81
	v_add_f32_e32 v77, v74, v77
	v_mov_b32_e32 v78, v90
	v_mov_b32_e32 v79, v91
	v_mov_b32_e32 v80, v92
	v_mov_b32_e32 v81, v93
	v_mul_f32_e32 v79, v69, v79
	v_fmac_f32_e32 v79, v66, v78
	v_fmac_f32_e32 v79, v67, v80
	v_fmac_f32_e32 v79, v68, v81
	v_add_f32_e32 v77, v77, v79
	v_mov_b32_e32 v78, v94
	v_mov_b32_e32 v79, v95
	v_mov_b32_e32 v80, v96
	v_mov_b32_e32 v81, v97
	v_mul_f32_e32 v79, v65, v79
	v_fmac_f32_e32 v79, v28, v78
	v_fmac_f32_e32 v79, v29, v80
	v_fmac_f32_e32 v79, v64, v81
	v_add_f32_e32 v77, v77, v79
	v_mov_b32_e32 v78, v98
	v_mov_b32_e32 v79, v99
	v_mov_b32_e32 v80, v100
	v_mov_b32_e32 v81, v101
	v_mul_f32_e32 v79, v61, v79
	v_fmac_f32_e32 v79, v43, v78
	v_fmac_f32_e32 v79, v60, v80
	v_fmac_f32_e32 v79, v41, v81
	v_add_f32_e32 v77, v77, v79
	v_min_f32_e32 v78, 0, v77
	v_mul_f32_e64 v77, |v77|, s26
	v_exp_f32_e32 v77, v77
	s_nop 0
	v_add_f32_e32 v77, 1.0, v77
	v_cmp_gt_f32_e64 s[52:53], s19, v77
	s_nop 1
	v_cndmask_b32_e64 v79, 0, 32, s[52:53]
	v_ldexp_f32 v77, v77, v79
	v_log_f32_e32 v77, v77
	s_nop 0
	v_mul_f32_e32 v79, 0x3f317217, v77
	v_fma_f32 v79, v77, s27, -v79
	v_fmac_f32_e32 v79, 0x3377d1cf, v77
	v_fmac_f32_e32 v79, 0x3f317217, v77
	v_cmp_lt_f32_e64 s[54:55], |v77|, s28
	s_nop 1
	v_cndmask_b32_e64 v77, v77, v79, s[54:55]
	v_cndmask_b32_e64 v79, 0, v228, s[52:53]
	v_sub_f32_e32 v77, v77, v79
	v_sub_f32_e32 v77, v78, v77
	v_or_b32_e32 v78, 5, v42
	v_mad_i64_i32 v[78:79], s[34:35], v78, s20, v[26:27]
	v_add_co_u32_e64 v82, s[52:53], s13, v78
	v_fmamk_f32 v77, v77, 0x3d800000, v76
	s_nop 0
	v_addc_co_u32_e64 v83, s[52:53], 0, v79, s[52:53]
	s_waitcnt vmcnt(8) lgkmcnt(0)
	v_mov_b32_e32 v78, v102
	v_mov_b32_e32 v79, v103
	v_mov_b32_e32 v80, v104
	v_mov_b32_e32 v81, v105
	v_mul_f32_e32 v79, v73, v79
	v_fmac_f32_e32 v79, v70, v78
	v_fmac_f32_e32 v79, v71, v80
	v_fmac_f32_e32 v79, v72, v81
	v_add_f32_e32 v84, v74, v79
	v_mov_b32_e32 v78, v106
	v_mov_b32_e32 v79, v107
	v_mov_b32_e32 v80, v108
	v_mov_b32_e32 v81, v109
	v_mul_f32_e32 v79, v69, v79
	v_fmac_f32_e32 v79, v66, v78
	v_fmac_f32_e32 v79, v67, v80
	v_fmac_f32_e32 v79, v68, v81
	v_add_f32_e32 v84, v84, v79
	v_mov_b32_e32 v78, v110
	v_mov_b32_e32 v79, v111
	v_mov_b32_e32 v80, v112
	v_mov_b32_e32 v81, v113
	v_mul_f32_e32 v79, v65, v79
	v_fmac_f32_e32 v79, v28, v78
	v_fmac_f32_e32 v79, v29, v80
	v_fmac_f32_e32 v79, v64, v81
	v_add_f32_e32 v84, v84, v79
	v_mov_b32_e32 v78, v114
	v_mov_b32_e32 v79, v115
	v_mov_b32_e32 v80, v116
	v_mov_b32_e32 v81, v117
	v_mul_f32_e32 v79, v61, v79
	v_fmac_f32_e32 v79, v43, v78
	v_fmac_f32_e32 v79, v60, v80
	v_fmac_f32_e32 v79, v41, v81
	v_add_f32_e32 v78, v84, v79
	v_min_f32_e32 v79, 0, v78
	v_mul_f32_e64 v78, |v78|, s26
	v_exp_f32_e32 v78, v78
	s_nop 0
	v_add_f32_e32 v78, 1.0, v78
	v_cmp_gt_f32_e64 s[52:53], s19, v78
	s_nop 1
	v_cndmask_b32_e64 v80, 0, 32, s[52:53]
	v_ldexp_f32 v78, v78, v80
	v_log_f32_e32 v78, v78
	s_nop 0
	v_mul_f32_e32 v80, 0x3f317217, v78
	v_fma_f32 v80, v78, s27, -v80
	v_fmac_f32_e32 v80, 0x3377d1cf, v78
	v_fmac_f32_e32 v80, 0x3f317217, v78
	v_cmp_lt_f32_e64 s[54:55], |v78|, s28
	s_nop 1
	v_cndmask_b32_e64 v78, v78, v80, s[54:55]
	v_cndmask_b32_e64 v80, 0, v228, s[52:53]
	v_sub_f32_e32 v78, v78, v80
	v_sub_f32_e32 v78, v79, v78
	v_or_b32_e32 v79, 6, v42
	v_mad_i64_i32 v[80:81], s[34:35], v79, s20, v[26:27]
	v_add_co_u32_e64 v84, s[52:53], s13, v80
	v_fmamk_f32 v78, v78, 0x3d800000, v77
	s_nop 0
	v_addc_co_u32_e64 v85, s[52:53], 0, v81, s[52:53]
	s_waitcnt vmcnt(4) lgkmcnt(0)
	v_mov_b32_e32 v80, v118
	v_mov_b32_e32 v81, v119
	v_mov_b32_e32 v82, v120
	v_mov_b32_e32 v83, v121
	v_mul_f32_e32 v79, v73, v81
	v_fmac_f32_e32 v79, v70, v80
	v_fmac_f32_e32 v79, v71, v82
	v_fmac_f32_e32 v79, v72, v83
	v_add_f32_e32 v79, v74, v79
	v_mov_b32_e32 v80, v122
	v_mov_b32_e32 v81, v123
	v_mov_b32_e32 v82, v124
	v_mov_b32_e32 v83, v125
	v_mul_f32_e32 v81, v69, v81
	v_fmac_f32_e32 v81, v66, v80
	v_fmac_f32_e32 v81, v67, v82
	v_fmac_f32_e32 v81, v68, v83
	v_add_f32_e32 v79, v79, v81
	v_mov_b32_e32 v80, v126
	v_mov_b32_e32 v81, v127
	v_mov_b32_e32 v82, v128
	v_mov_b32_e32 v83, v129
	v_mul_f32_e32 v81, v65, v81
	v_fmac_f32_e32 v81, v28, v80
	v_fmac_f32_e32 v81, v29, v82
	v_fmac_f32_e32 v81, v64, v83
	v_add_f32_e32 v79, v79, v81
	v_mov_b32_e32 v80, v130
	v_mov_b32_e32 v81, v131
	v_mov_b32_e32 v82, v132
	v_mov_b32_e32 v83, v133
	v_mul_f32_e32 v81, v61, v81
	v_fmac_f32_e32 v81, v43, v80
	v_fmac_f32_e32 v81, v60, v82
	v_fmac_f32_e32 v81, v41, v83
	v_add_f32_e32 v79, v79, v81
	v_min_f32_e32 v80, 0, v79
	v_mul_f32_e64 v79, |v79|, s26
	v_exp_f32_e32 v79, v79
	s_nop 0
	v_add_f32_e32 v79, 1.0, v79
	v_cmp_gt_f32_e64 s[52:53], s19, v79
	s_nop 1
	v_cndmask_b32_e64 v81, 0, 32, s[52:53]
	v_ldexp_f32 v79, v79, v81
	v_log_f32_e32 v79, v79
	s_nop 0
	v_mul_f32_e32 v81, 0x3f317217, v79
	v_fma_f32 v81, v79, s27, -v81
	v_fmac_f32_e32 v81, 0x3377d1cf, v79
	v_fmac_f32_e32 v81, 0x3f317217, v79
	v_cmp_lt_f32_e64 s[54:55], |v79|, s28
	s_nop 1
	v_cndmask_b32_e64 v79, v79, v81, s[54:55]
	v_cndmask_b32_e64 v81, 0, v228, s[52:53]
	v_sub_f32_e32 v79, v79, v81
	v_sub_f32_e32 v79, v80, v79
	v_or_b32_e32 v80, 7, v42
	v_mad_i64_i32 v[26:27], s[34:35], v80, s20, v[26:27]
	v_add_co_u32_e64 v26, s[52:53], s13, v26
	v_fmamk_f32 v79, v79, 0x3d800000, v78
	s_nop 0
	v_addc_co_u32_e64 v27, s[52:53], 0, v27, s[52:53]
	s_waitcnt vmcnt(0) lgkmcnt(0)
	v_mov_b32_e32 v80, v134
	v_mov_b32_e32 v81, v135
	v_mov_b32_e32 v82, v136
	v_mov_b32_e32 v83, v137
	v_mul_f32_e32 v73, v73, v81
	v_fmac_f32_e32 v73, v70, v80
	v_fmac_f32_e32 v73, v71, v82
	v_fmac_f32_e32 v73, v72, v83
	v_add_f32_e32 v74, v74, v73
	v_mov_b32_e32 v70, v138
	v_mov_b32_e32 v71, v139
	v_mov_b32_e32 v72, v140
	v_mov_b32_e32 v73, v141
	v_mul_f32_e32 v69, v69, v71
	v_fmac_f32_e32 v69, v66, v70
	v_fmac_f32_e32 v69, v67, v72
	v_fmac_f32_e32 v69, v68, v73
	v_add_f32_e32 v70, v74, v69
	v_mov_b32_e32 v66, v142
	v_mov_b32_e32 v67, v143
	v_mov_b32_e32 v68, v144
	v_mov_b32_e32 v69, v145
	v_mul_f32_e32 v65, v65, v67
	v_fmac_f32_e32 v65, v28, v66
	v_fmac_f32_e32 v65, v29, v68
	v_fmac_f32_e32 v65, v64, v69
	v_add_f32_e32 v64, v70, v65
	v_mov_b32_e32 v26, v146
	v_mov_b32_e32 v27, v147
	v_mov_b32_e32 v28, v148
	v_mov_b32_e32 v29, v149
	v_mul_f32_e32 v27, v61, v27
	v_fmac_f32_e32 v27, v43, v26
	v_fmac_f32_e32 v27, v60, v28
	v_fmac_f32_e32 v27, v41, v29
	v_add_f32_e32 v26, v64, v27
	v_min_f32_e32 v27, 0, v26
	v_mul_f32_e64 v26, |v26|, s26
	v_exp_f32_e32 v26, v26
	s_nop 0
	v_add_f32_e32 v26, 1.0, v26
	v_cmp_gt_f32_e64 s[52:53], s19, v26
	s_nop 1
	v_cndmask_b32_e64 v28, 0, 32, s[52:53]
	v_ldexp_f32 v26, v26, v28
	v_log_f32_e32 v26, v26
	s_nop 0
	v_mul_f32_e32 v28, 0x3f317217, v26
	v_fma_f32 v28, v26, s27, -v28
	v_fmac_f32_e32 v28, 0x3377d1cf, v26
	v_fmac_f32_e32 v28, 0x3f317217, v26
	v_cmp_lt_f32_e64 s[54:55], |v26|, s28
	s_nop 1
	v_cndmask_b32_e64 v26, v26, v28, s[54:55]
	v_cndmask_b32_e64 v28, 0, v228, s[52:53]
	v_sub_f32_e32 v26, v26, v28
	v_sub_f32_e32 v26, v27, v26
	v_fmamk_f32 v26, v26, 0x3d800000, v79
	v_mov_b32_e32 v27, 0
	v_mov_b32_e32 v28, 0
	ds_write_b32 v46, v26 offset:32768
	s_waitcnt lgkmcnt(0)
	s_barrier
	s_and_saveexec_b64 s[52:53], vcc
	s_cbranch_execz .LBB0_1041
	ds_read_b32 v28, v47 offset:32768
	s_waitcnt lgkmcnt(0)
	v_add_f32_e32 v28, 0, v28
	s_or_b64 exec, exec, s[52:53]
	v_mov_b32_e32 v29, 0
	s_and_saveexec_b64 s[52:53], s[38:39]
	s_cbranch_execnz .LBB0_1042
